# v60 + mLSTM decay-mask tile build: straight-line (v_cndmask masks) with packed dword LDS writes instead of 8 exec-masked blocks with 2-byte writes
# speedup vs baseline: 1.0004x; 1.0004x over previous
; #define LAS __attribute__((address_space(3)))
; __device__ __forceinline__ void mlstm_item(const P& p, const Ctx& c, int seg, int w, bool save) {
;     ...
;             { const int t = tidv >> 3, part = tidv & 7;
;               const u32x4 q0 = *(const LAS u32x4*)(Qs + t * 136 + part * 16), q1 = *(const LAS u32x4*)(Qs + t * 136 + part * 16 + 8);
;               const LAS float* np = nold + d0 + part * 16; const f32x4 n0 = *(const LAS f32x4*)np, n1 = *(const LAS f32x4*)(np + 4), n2 = *(const LAS f32x4*)(np + 8), n3 = *(const LAS f32x4*)(np + 12);
;               qnacc += bflo(q0.x) * n0[0] + bfhi(q0.x) * n0[1] + bflo(q0.y) * n0[2] + bfhi(q0.y) * n0[3] + bflo(q0.z) * n1[0] + bfhi(q0.z) * n1[1] + bflo(q0.w) * n1[2] + bfhi(q0.w) * n1[3]
;                      + bflo(q1.x) * n2[0] + bfhi(q1.x) * n2[1] + bflo(q1.y) * n2[2] + bfhi(q1.y) * n2[3] + bflo(q1.z) * n3[0] + bfhi(q1.z) * n3[1] + bflo(q1.w) * n3[2] + bfhi(q1.w) * n3[3]; }
;             { const int dd = tidv >> 2, part = tidv & 3;
;               const u32x4 k0 = *(const LAS u32x4*)(KTs + dd * 72 + part * 16), k1 = *(const LAS u32x4*)(KTs + dd * 72 + part * 16 + 8);
;               const LAS float* wp = wgt + part * 16; const f32x4 w0 = *(const LAS f32x4*)wp, w1 = *(const LAS f32x4*)(wp + 4), w2 = *(const LAS f32x4*)(wp + 8), w3 = *(const LAS f32x4*)(wp + 12);
;               float a = bflo(k0.x) * w0[0] + bfhi(k0.x) * w0[1] + bflo(k0.y) * w0[2] + bfhi(k0.y) * w0[3] + bflo(k0.z) * w1[0] + bfhi(k0.z) * w1[1] + bflo(k0.w) * w1[2] + bfhi(k0.w) * w1[3]
;                       + bflo(k1.x) * w2[0] + bfhi(k1.x) * w2[1] + bflo(k1.y) * w2[2] + bfhi(k1.y) * w2[3] + bflo(k1.z) * w3[0] + bfhi(k1.z) * w3[1] + bflo(k1.w) * w3[2] + bfhi(k1.w) * w3[3];
;               a = dpp_add<0xB1>(a); a = dpp_add<0x4E>(a);
;               if (part == 0) nnew[d0 + dd] = gtot * nold[d0 + dd] + a; }
;         }
;         qnacc = dpp_add<0xB1>(qnacc); qnacc = dpp_add<0x4E>(qnacc); qnacc = dpp_add<0x141>(qnacc);
;         if ((tidv & 7) == 0) qn[tidv >> 3] = qnacc;
; #pragma unroll
;         for (int x = 0; x < 2; ++x) { const int ti = c.wv * 2 + x, tm = ti >> 2, tn = ti & 3; const int s = tn * 16 + l15; const float bs = bcum[s] - ipr[s];
; #pragma unroll
;             for (int jj = 0; jj < 4; ++jj) { const int t = tm * 16 + quad * 4 + jj; const float v = (s <= t) ? Sa[x][jj] * __expf(bcum[t] - bs) : 0.f; Sp[t * 72 + s] = f2bf(v); } }
.LBB0_381:
	s_or_b64 exec, exec, s[16:17]
	v_lshlrev_b32_e32 v4, 16, v94
	v_and_b32_e32 v94, 0xffff0000, v94
	v_mul_f32_e32 v94, v103, v94
	v_fmac_f32_e32 v94, v102, v4
	v_lshlrev_b32_e32 v4, 16, v95
	v_fmac_f32_e32 v94, v104, v4
	v_and_b32_e32 v4, 0xffff0000, v95
	v_fmac_f32_e32 v94, v105, v4
	v_lshlrev_b32_e32 v4, 16, v96
	v_fmac_f32_e32 v94, v98, v4
	v_and_b32_e32 v4, 0xffff0000, v96
	v_fmac_f32_e32 v94, v99, v4
	v_lshlrev_b32_e32 v4, 16, v97
	v_fmac_f32_e32 v94, v100, v4
	v_and_b32_e32 v4, 0xffff0000, v97
	v_fmac_f32_e32 v94, v101, v4
	v_lshlrev_b32_e32 v4, 16, v82
	v_fmac_f32_e32 v94, v90, v4
	v_and_b32_e32 v4, 0xffff0000, v82
	v_fmac_f32_e32 v94, v91, v4
	v_lshlrev_b32_e32 v4, 16, v83
	v_fmac_f32_e32 v94, v92, v4
	v_and_b32_e32 v4, 0xffff0000, v83
	v_and_b32_e32 v83, 0xffff0000, v118
	v_lshlrev_b32_e32 v82, 16, v118
	v_mul_f32_e32 v83, v127, v83
	v_fmac_f32_e32 v83, v126, v82
	v_lshlrev_b32_e32 v82, 16, v119
	v_fmac_f32_e32 v83, v128, v82
	v_and_b32_e32 v82, 0xffff0000, v119
	v_fmac_f32_e32 v83, v129, v82
	v_lshlrev_b32_e32 v82, 16, v120
	v_fmac_f32_e32 v83, v122, v82
	v_and_b32_e32 v82, 0xffff0000, v120
	v_fmac_f32_e32 v83, v123, v82
	v_lshlrev_b32_e32 v82, 16, v121
	v_fmac_f32_e32 v83, v124, v82
	v_and_b32_e32 v82, 0xffff0000, v121
	v_fmac_f32_e32 v83, v125, v82
	v_lshlrev_b32_e32 v82, 16, v106
	v_fmac_f32_e32 v83, v114, v82
	v_and_b32_e32 v82, 0xffff0000, v106
	v_fmac_f32_e32 v83, v115, v82
	v_lshlrev_b32_e32 v82, 16, v107
	v_fmac_f32_e32 v94, v93, v4
	v_lshlrev_b32_e32 v4, 16, v84
	v_fmac_f32_e32 v83, v116, v82
	v_and_b32_e32 v82, 0xffff0000, v107
	v_fmac_f32_e32 v94, v86, v4
	v_and_b32_e32 v4, 0xffff0000, v84
	v_fmac_f32_e32 v83, v117, v82
	v_lshlrev_b32_e32 v82, 16, v108
	v_fmac_f32_e32 v94, v87, v4
	v_lshlrev_b32_e32 v4, 16, v85
	v_fmac_f32_e32 v83, v110, v82
	v_and_b32_e32 v82, 0xffff0000, v108
	v_fmac_f32_e32 v94, v88, v4
	v_and_b32_e32 v4, 0xffff0000, v85
	v_fmac_f32_e32 v83, v111, v82
	v_lshlrev_b32_e32 v82, 16, v109
	v_fmac_f32_e32 v94, v89, v4
	v_fmac_f32_e32 v83, v112, v82
	v_and_b32_e32 v82, 0xffff0000, v109
	v_add_f32_e32 v4, 0, v94
	v_fmac_f32_e32 v83, v113, v82
	v_add_f32_e32 v4, v4, v83
	v_and_b32_e32 v83, 0xffff0000, v154
	v_lshlrev_b32_e32 v82, 16, v154
	v_mul_f32_e32 v83, v167, v83
	v_fmac_f32_e32 v83, v166, v82
	v_lshlrev_b32_e32 v82, 16, v155
	v_fmac_f32_e32 v83, v168, v82
	v_and_b32_e32 v82, 0xffff0000, v155
	v_fmac_f32_e32 v83, v169, v82
	v_lshlrev_b32_e32 v82, 16, v156
	v_fmac_f32_e32 v83, v162, v82
	v_and_b32_e32 v82, 0xffff0000, v156
	v_fmac_f32_e32 v83, v163, v82
	v_lshlrev_b32_e32 v82, 16, v157
	v_fmac_f32_e32 v83, v164, v82
	v_and_b32_e32 v82, 0xffff0000, v157
	v_fmac_f32_e32 v83, v165, v82
	v_lshlrev_b32_e32 v82, 16, v146
	v_fmac_f32_e32 v83, v158, v82
	v_and_b32_e32 v82, 0xffff0000, v146
	v_fmac_f32_e32 v83, v159, v82
	v_lshlrev_b32_e32 v82, 16, v147
	v_fmac_f32_e32 v83, v160, v82
	v_and_b32_e32 v82, 0xffff0000, v147
	v_fmac_f32_e32 v83, v161, v82
	v_lshlrev_b32_e32 v82, 16, v148
	v_fmac_f32_e32 v83, v150, v82
	v_and_b32_e32 v82, 0xffff0000, v148
	v_fmac_f32_e32 v83, v151, v82
	v_lshlrev_b32_e32 v82, 16, v149
	v_fmac_f32_e32 v83, v152, v82
	v_and_b32_e32 v82, 0xffff0000, v149
	v_fmac_f32_e32 v83, v153, v82
	v_add_f32_e32 v4, v4, v83
	v_and_b32_e32 v83, 7, v191
	v_cmp_eq_u32_e32 vcc, 0, v83
	v_add_f32_dpp v4, v4, v4 quad_perm:[1,0,3,2] row_mask:0xf bank_mask:0xf bound_ctrl:1
	s_nop 1
	v_add_f32_dpp v4, v4, v4 quad_perm:[2,3,0,1] row_mask:0xf bank_mask:0xf bound_ctrl:1
	s_nop 1
	v_mov_b32_dpp v82, v4 row_half_mirror row_mask:0xf bank_mask:0xf bound_ctrl:1
	s_and_saveexec_b64 s[16:17], vcc
	v_add_f32_e32 v4, v4, v82
	v_ashrrev_i32_e32 v82, 1, v191
	v_add_u32_e32 v82, 0, v82
	v_add_u32_e32 v82, 0x20400, v82
	ds_write_b32 v82, v4
	s_or_b64 exec, exec, s[16:17]
	v_add_u32_e32 v234, s21, v192
	v_lshl_add_u32 v234, v234, 2, 0
	v_add_u32_e32 v234, 0x20000, v234
	ds_read_b128 v[236:239], v234
	v_lshl_add_u32 v235, v194, 2, 0
	v_add_u32_e32 v240, 0x20000, v235
	v_add_u32_e32 v235, 0x20100, v235
	ds_read_b32 v240, v240
	ds_read_b32 v241, v235
	v_lshl_add_u32 v4, v193, 2, 0
	v_add_u32_e32 v82, 0x20000, v4
	v_add_u32_e32 v4, 0x20100, v4
	ds_read_b32 v84, v82
	ds_read_b32 v4, v4
	v_add_u32_e32 v82, s21, v192
	v_or_b32_e32 v87, 1, v82
	v_or_b32_e32 v90, 2, v82
	v_or_b32_e32 v92, 3, v82
	v_mul_lo_u32 v86, v82, s63
	v_and_b32_e32 v242, 1, v180
	v_cmp_ne_u32_e64 s[16:17], 0, v242
	v_mov_b32_e32 v243, 0x5040100
	v_mov_b32_e32 v244, 0x3020706
	v_mul_u32_u24_e32 v242, 0x11e, v242
	v_cndmask_b32_e64 v243, v243, v244, s[16:17]
	v_lshl_add_u32 v94, v193, 1, s0
	v_lshlrev_b32_e32 v95, 1, v194
	v_add3_u32 v245, v94, v86, v242
	v_add3_u32 v246, s0, v86, v95
	v_add_u32_e32 v246, v246, v242
	s_waitcnt lgkmcnt(0)
; #define LAS __attribute__((address_space(3)))
; __device__ __forceinline__ bf16_t f2bf(float f) { const __bf16 r = (__bf16)f; bf16_t u; __builtin_memcpy(&u, &r, 2); return u; }
; __device__ __forceinline__ float bflo(unsigned u) { return __uint_as_float(u << 16); }
; __device__ __forceinline__ float bfhi(unsigned u) { return __uint_as_float(u & 0xFFFF0000u); }
; __device__ __forceinline__ float frcp(float x) { return __builtin_amdgcn_rcpf(x); }
; __device__ __forceinline__ void lds_barrier() { asm volatile("s_waitcnt lgkmcnt(0)" ::: "memory"); __builtin_amdgcn_s_barrier(); asm volatile("" ::: "memory"); }
; __device__ __forceinline__ void mlstm_item(const P& p, const Ctx& c, int seg, int w, bool save) {
;     ...
; #pragma unroll
;         for (int x = 0; x < 2; ++x) { const int ti = c.wv * 2 + x, tm = ti >> 2, tn = ti & 3; const int s = tn * 16 + l15; const float bs = bcum[s] - ipr[s];
; #pragma unroll
;             for (int jj = 0; jj < 4; ++jj) { const int t = tm * 16 + quad * 4 + jj; const float v = (s <= t) ? Sa[x][jj] * __expf(bcum[t] - bs) : 0.f; Sp[t * 72 + s] = f2bf(v); } }
;         lds_barrier();
;         { const int t = tidv >> 3, part = tidv & 7; const u32x4 sr = *(const LAS u32x4*)(Sp + t * 72 + part * 8);
;           float ds = bflo(sr.x) + bfhi(sr.x) + bflo(sr.y) + bfhi(sr.y) + bflo(sr.z) + bfhi(sr.z) + bflo(sr.w) + bfhi(sr.w);
;           ds = dpp_add<0xB1>(ds); ds = dpp_add<0x4E>(ds); ds = dpp_add<0x141>(ds);
;           if (part == 0) { const float den = ds + gin[t] * qn[t]; rden[t] = frcp(fmaxf(fabsf(den), 1.0f)); } }
	v_sub_f32_e32 v93, v84, v4
	v_sub_f32_e32 v247, v240, v241
	v_lshl_add_u32 v4, v82, 2, 0
	v_sub_f32_e32 v84, v236, v93
	v_sub_f32_e32 v85, v237, v93
	v_sub_f32_e32 v88, v238, v93
	v_sub_f32_e32 v89, v239, v93
	v_sub_f32_e32 v96, v236, v247
	v_sub_f32_e32 v97, v237, v247
	v_sub_f32_e32 v248, v238, v247
	v_sub_f32_e32 v249, v239, v247
	v_mul_f32_e32 v84, 0x3fb8aa3b, v84
	v_mul_f32_e32 v85, 0x3fb8aa3b, v85
	v_mul_f32_e32 v88, 0x3fb8aa3b, v88
	v_mul_f32_e32 v89, 0x3fb8aa3b, v89
	v_mul_f32_e32 v96, 0x3fb8aa3b, v96
	v_mul_f32_e32 v97, 0x3fb8aa3b, v97
	v_mul_f32_e32 v248, 0x3fb8aa3b, v248
	v_mul_f32_e32 v249, 0x3fb8aa3b, v249
	v_exp_f32_e32 v84, v84
	v_exp_f32_e32 v85, v85
	v_exp_f32_e32 v88, v88
	v_exp_f32_e32 v89, v89
	v_exp_f32_e32 v96, v96
	v_exp_f32_e32 v97, v97
	v_exp_f32_e32 v248, v248
	v_exp_f32_e32 v249, v249
	v_mul_f32_e32 v84, v142, v84
	v_mul_f32_e32 v85, v143, v85
	v_mul_f32_e32 v88, v144, v88
	v_mul_f32_e32 v89, v145, v89
	v_mul_f32_e32 v96, v138, v96
	v_mul_f32_e32 v97, v139, v97
	v_mul_f32_e32 v248, v140, v248
	v_mul_f32_e32 v249, v141, v249
	v_cmp_le_i32_e64 s[16:17], v193, v82
	v_cmp_le_i32_e64 s[88:89], v193, v87
	v_cndmask_b32_e64 v84, 0, v84, s[16:17]
	v_cndmask_b32_e64 v85, 0, v85, s[88:89]
	v_cmp_le_i32_e64 s[16:17], v193, v90
	v_cmp_le_i32_e64 s[88:89], v193, v92
	v_cndmask_b32_e64 v88, 0, v88, s[16:17]
	v_cndmask_b32_e64 v89, 0, v89, s[88:89]
	v_cmp_le_i32_e64 s[16:17], v194, v82
	v_cmp_le_i32_e64 s[88:89], v194, v87
	v_cndmask_b32_e64 v96, 0, v96, s[16:17]
	v_cndmask_b32_e64 v97, 0, v97, s[88:89]
	v_cmp_le_i32_e64 s[16:17], v194, v90
	v_cmp_le_i32_e64 s[88:89], v194, v92
	v_cndmask_b32_e64 v248, 0, v248, s[16:17]
	v_cndmask_b32_e64 v249, 0, v249, s[88:89]
	v_cvt_pk_bf16_f32 v84, v84, v88
	v_cvt_pk_bf16_f32 v85, v85, v89
	v_cvt_pk_bf16_f32 v96, v96, v248
	v_cvt_pk_bf16_f32 v97, v97, v249
	v_mov_b32_dpp v250, v84 quad_perm:[1,0,3,2] row_mask:0xf bank_mask:0xf bound_ctrl:1
	v_mov_b32_dpp v251, v85 quad_perm:[1,0,3,2] row_mask:0xf bank_mask:0xf bound_ctrl:1
	v_mov_b32_dpp v252, v96 quad_perm:[1,0,3,2] row_mask:0xf bank_mask:0xf bound_ctrl:1
	v_mov_b32_dpp v253, v97 quad_perm:[1,0,3,2] row_mask:0xf bank_mask:0xf bound_ctrl:1
	v_perm_b32 v84, v250, v84, v243
	v_perm_b32 v85, v251, v85, v243
	v_perm_b32 v96, v252, v96, v243
	v_perm_b32 v97, v253, v97, v243
	ds_write_b32 v245, v84
	ds_write_b32 v245, v85 offset:144
	ds_write_b32 v246, v96
	ds_write_b32 v246, v97 offset:144
	v_lshlrev_b32_e32 v83, 4, v83
	s_waitcnt lgkmcnt(0)
	s_barrier
	v_add3_u32 v83, s0, v195, v83
	ds_read_b128 v[84:87], v83
	s_waitcnt lgkmcnt(0)
	v_lshlrev_b32_e32 v83, 16, v84
	v_and_b32_e32 v84, 0xffff0000, v84
	v_add_f32_e32 v83, v83, v84
	v_lshlrev_b32_e32 v84, 16, v85
	v_add_f32_e32 v83, v83, v84
	v_and_b32_e32 v84, 0xffff0000, v85
	v_add_f32_e32 v83, v83, v84
	v_lshlrev_b32_e32 v84, 16, v86
	v_add_f32_e32 v83, v83, v84
	v_and_b32_e32 v84, 0xffff0000, v86
	v_add_f32_e32 v83, v83, v84
	v_lshlrev_b32_e32 v84, 16, v87
	v_add_f32_e32 v83, v83, v84
	v_and_b32_e32 v84, 0xffff0000, v87
	v_add_f32_e32 v83, v83, v84
	s_nop 1
	v_add_f32_dpp v83, v83, v83 quad_perm:[1,0,3,2] row_mask:0xf bank_mask:0xf bound_ctrl:1
	s_nop 1
	v_add_f32_dpp v83, v83, v83 quad_perm:[2,3,0,1] row_mask:0xf bank_mask:0xf bound_ctrl:1
	s_nop 1
	v_mov_b32_dpp v84, v83 row_half_mirror row_mask:0xf bank_mask:0xf bound_ctrl:1
	s_and_saveexec_b64 s[16:17], vcc
	s_cbranch_execz .LBB0_401
	v_add_f32_e32 v83, v83, v84
	v_lshl_add_u32 v84, v184, 2, 0
	v_add_u32_e32 v85, 0x20300, v84
	v_add_u32_e32 v86, 0x20400, v84
	ds_read_b32 v85, v85
	ds_read_b32 v86, v86
	v_add_u32_e32 v84, 0x20500, v84
	s_waitcnt lgkmcnt(0)
	v_fmac_f32_e32 v83, v85, v86
	v_max_f32_e64 v83, |v83|, 1.0
	v_rcp_f32_e32 v83, v83
	ds_write_b32 v84, v83
